# FF2 (layer 0): the 32 third-round tiles run as 64 half-tile units (128 rows, ai=0 MFMA segments only) on blocks 0-63; next-layer weight conversion moved to blocks >= 64
# baseline (speedup 1.0000x reference)
.LBB0_54:
	s_load_dwordx2 s[22:23], s[0:1], 0x118
	s_load_dwordx4 s[4:7], s[0:1], 0xf8
	s_waitcnt lgkmcnt(0)
	s_mov_b32 s5, s86
	s_lshl_b32 s26, s21, 3
	s_load_dword s4, s[0:1], 0x110
	s_mov_b32 s33, s22
	s_mov_b64 s[2:3], s[6:7]
	s_add_u32 s2, s2, 0xd723c00
	s_addc_u32 s3, s3, 0
	v_writelane_b32 v252, s2, 6
	s_cmpk_lt_i32 s33, 0x41
	s_mov_b32 s25, 0
	v_writelane_b32 v252, s3, 7
	s_cselect_b64 s[2:3], -1, 0
	v_writelane_b32 v252, s2, 8
	s_lshl_b32 s28, s33, 3
	s_lshl_b32 s30, s33, 9
	v_writelane_b32 v252, s3, 9
	s_add_u32 s2, s70, 0x200
	s_addc_u32 s3, s71, 0
	v_writelane_b32 v252, s2, 10
	v_mov_b32_e32 v161, 0
	v_mov_b32_e32 v191, 0x358637bd
	v_writelane_b32 v252, s3, 11
	s_add_u32 s2, s70, 0x1000
	s_addc_u32 s3, s71, 0
	v_writelane_b32 v252, s2, 12
	v_mov_b32_e32 v193, 0x3ecc95a3
	v_mov_b32_e32 v194, 0x3ca908c9
	v_writelane_b32 v252, s3, 13
	s_add_u32 s2, s70, 0x1100
	s_addc_u32 s3, s71, 0
	v_writelane_b32 v252, s2, 14
	v_mov_b32_e32 v163, 0xbdd53b94
	v_mov_b32_e32 v218, 0xffffce40
	v_writelane_b32 v252, s3, 15
	s_add_u32 s2, s70, 0x1200
	s_addc_u32 s3, s71, 0
	v_writelane_b32 v252, s2, 16
	v_mov_b32_e32 v219, 0xffffcc40
	v_mov_b32_e32 v220, 0xffffc840
	v_writelane_b32 v252, s3, 17
	s_add_u32 s2, s70, 0x1300
	s_addc_u32 s3, s71, 0
	v_writelane_b32 v252, s2, 18
	s_cmp_eq_u32 s20, 15
	v_mov_b32_e32 v221, 0xffffc440
	v_writelane_b32 v252, s3, 19
	s_cselect_b64 s[2:3], -1, 0
	v_writelane_b32 v252, s2, 20
	s_cmp_eq_u32 s20, 14
	v_mov_b32_e32 v222, 0xffffc040
	v_writelane_b32 v252, s3, 21
	s_cselect_b64 s[2:3], -1, 0
	v_writelane_b32 v252, s2, 22
	s_cmp_eq_u32 s20, 13
	v_mov_b32_e32 v223, 0xffffb840
	v_writelane_b32 v252, s3, 23
	s_cselect_b64 s[2:3], -1, 0
	v_writelane_b32 v252, s2, 24
	s_cmp_eq_u32 s20, 12
	v_mov_b32_e32 v224, 0xffff9840
	v_writelane_b32 v252, s3, 25
	s_cselect_b64 s[2:3], -1, 0
	v_writelane_b32 v252, s2, 26
	s_cmp_eq_u32 s20, 11
	v_mov_b64_e32 v[164:165], 0x198
	v_writelane_b32 v252, s3, 27
	s_cselect_b64 s[2:3], -1, 0
	v_writelane_b32 v252, s2, 28
	s_cmp_eq_u32 s20, 10
	v_mov_b64_e32 v[166:167], 0x197
	v_writelane_b32 v252, s3, 29
	s_cselect_b64 s[2:3], -1, 0
	v_writelane_b32 v252, s2, 30
	s_cmp_eq_u32 s20, 9
	v_mov_b32_e32 v228, 0x4000
	v_writelane_b32 v252, s3, 31
	s_cselect_b64 s[2:3], -1, 0
	v_writelane_b32 v252, s2, 32
	s_cmp_eq_u32 s20, 8
	v_mov_b32_e32 v229, 0xffffff00
	v_writelane_b32 v252, s3, 33
	s_cselect_b64 s[2:3], -1, 0
	v_writelane_b32 v252, s2, 34
	s_cmp_eq_u32 s20, 7
	v_mov_b32_e32 v231, 0x7f800000
	v_writelane_b32 v252, s3, 35
	s_cselect_b64 s[2:3], -1, 0
	v_writelane_b32 v252, s2, 36
	s_cmp_eq_u32 s20, 6
	v_mov_b32_e32 v232, 0x7fc00000
	v_writelane_b32 v252, s3, 37
	s_cselect_b64 s[2:3], -1, 0
	v_writelane_b32 v252, s2, 38
	s_cmp_eq_u32 s20, 5
	v_mov_b32_e32 v233, 0xff800000
	v_writelane_b32 v252, s3, 39
	s_cselect_b64 s[2:3], -1, 0
	v_writelane_b32 v252, s2, 40
	s_cmp_eq_u32 s20, 4
	v_mov_b64_e32 v[168:169], 0x110
	v_writelane_b32 v252, s3, 41
	s_cselect_b64 s[2:3], -1, 0
	v_writelane_b32 v252, s2, 42
	s_cmp_eq_u32 s20, 3
	v_mov_b64_e32 v[170:171], 0x10f
	v_writelane_b32 v252, s3, 43
	s_cselect_b64 s[2:3], -1, 0
	v_writelane_b32 v252, s2, 44
	s_cmp_eq_u32 s20, 2
	s_movk_i32 s91, 0x110
	v_writelane_b32 v252, s3, 45
	s_cselect_b64 s[2:3], -1, 0
	v_writelane_b32 v252, s2, 46
	s_cmp_eq_u32 s20, 1
	s_movk_i32 s95, 0x3ff
	v_writelane_b32 v252, s3, 47
	s_cselect_b64 s[2:3], -1, 0
	v_writelane_b32 v252, s2, 48
	s_cmp_eq_u32 s20, 0
	s_movk_i32 s90, 0x7ff
	v_writelane_b32 v252, s3, 49
	s_cselect_b64 s[2:3], -1, 0
	v_writelane_b32 v252, s2, 50
	s_movk_i32 s87, 0x100
	s_movk_i32 s76, 0x7000
	v_writelane_b32 v252, s3, 51
	s_lshl_b32 s2, s20, 8
	s_add_u32 s2, s70, s2
	s_addc_u32 s3, s71, 0
	s_add_u32 s6, s2, 0x1400
	s_addc_u32 s7, s3, 0
	v_writelane_b32 v252, s6, 52
	s_add_u32 s2, s2, 0x2400
	s_addc_u32 s3, s3, 0
	v_writelane_b32 v252, s7, 53
	v_writelane_b32 v252, s2, 54
	s_movk_i32 s94, 0x4400
	s_movk_i32 s77, 0x8000
	v_writelane_b32 v252, s3, 55
	s_add_u32 s2, s70, 0x3400
	s_addc_u32 s3, s71, 0
	v_writelane_b32 v252, s2, 56
	s_mov_b32 s80, 0xbfb8aa3b
	s_mov_b32 s81, 0x3f2aaaab
	v_writelane_b32 v252, s3, 57
	s_add_u32 s2, s70, 0x3500
	s_addc_u32 s3, s71, 0
	v_writelane_b32 v252, s2, 58
	s_cmpk_lt_i32 s5, 0x484
	s_mov_b32 s84, 0x3f317218
	v_writelane_b32 v252, s3, 59
	s_cselect_b64 s[2:3], -1, 0
	v_writelane_b32 v252, s2, 60
	s_mov_b32 s85, 0x7f800000
	s_mov_b32 s88, 0x33800000
	v_writelane_b32 v252, s3, 61
	s_ashr_i32 s2, s5, 31
	v_writelane_b32 v252, s2, 62
	s_lshr_b32 s2, s2, 29
	s_add_i32 s2, s5, s2
	s_ashr_i32 s11, s2, 3
	s_and_b32 s2, s2, -8
	s_sub_i32 s20, s5, s2
	s_mul_i32 s2, s20, 0x90
	s_or_b32 s6, s2, 4
	s_ashr_i32 s2, s33, 31
	s_cmpk_lt_i32 s5, 0x198
	v_writelane_b32 v252, s2, 63
	s_cselect_b64 s[2:3], -1, 0
	v_writelane_b32 v253, s2, 0
	s_waitcnt lgkmcnt(0)
	s_bitcmp1_b32 s4, 0
	s_mov_b32 s89, 0x42ddb3d7
	v_writelane_b32 v253, s3, 1
	s_cselect_b64 s[2:3], -1, 0
	v_writelane_b32 v253, s2, 2
	s_bitcmp1_b32 s4, 1
	s_mov_b64 s[78:79], 0x14744d00
	v_writelane_b32 v253, s3, 3
	s_cselect_b64 s[2:3], -1, 0
	v_writelane_b32 v253, s2, 4
	s_bitcmp1_b32 s4, 2
	s_mov_b32 s72, s25
	v_writelane_b32 v253, s3, 5
	s_cselect_b64 s[2:3], -1, 0
	v_writelane_b32 v253, s2, 6
	s_cmpk_lt_i32 s5, 0x110
	s_nop 0
	v_writelane_b32 v253, s3, 7
	s_cselect_b64 s[2:3], -1, 0
	v_writelane_b32 v253, s2, 8
	s_bitcmp0_b32 s4, 4
	s_nop 0
	v_writelane_b32 v253, s3, 9
	s_cselect_b64 s[2:3], -1, 0
	v_writelane_b32 v253, s2, 10
	s_bitcmp1_b32 s4, 3
	s_nop 0
	v_writelane_b32 v253, s3, 11
	s_cselect_b64 s[2:3], -1, 0
	v_writelane_b32 v253, s2, 12
	s_nop 1
	v_writelane_b32 v253, s3, 13
	s_not_b32 s2, s4
	s_lshr_b32 s2, s2, 1
	s_and_b32 s7, s2, 4
	s_cmp_gt_i32 s5, 63
	s_cselect_b64 s[2:3], -1, 0
	s_cmp_gt_i32 s33, 64
	v_writelane_b32 v253, s5, 14
	s_cselect_b64 s[4:5], -1, 0
	s_and_b64 s[2:3], s[4:5], s[2:3]
	v_writelane_b32 v253, s2, 15
	s_nop 1
	v_writelane_b32 v253, s3, 16
	s_max_u32 s2, s7, 1
	v_writelane_b32 v253, s2, 17
	s_sub_i32 s2, s33, 64
	s_lshl_b32 s3, s2, 3
	v_writelane_b32 v253, s3, 18
	s_lshl_b32 s24, s2, 9
	v_writelane_b32 v253, s2, 19
	s_cmp_lt_i32 s20, 4
	s_mul_i32 s2, s20, 0x91
	s_cselect_b32 s2, s2, s6
	s_add_i32 s2, s2, s11
	s_mul_hi_i32 s3, s2, 0x78787879
	s_lshr_b32 s4, s3, 31
	s_ashr_i32 s3, s3, 6
	s_add_i32 s3, s3, s4
	s_mul_i32 s4, s3, 0x88
	s_lshl_b32 s5, s3, 3
	s_sub_i32 s4, s2, s4
	s_sub_i32 s2, 0x44, s5
	s_min_u32 s6, s2, 8
	s_cmp_lt_i32 s20, 0
	s_cselect_b64 s[2:3], -1, 0
	v_writelane_b32 v253, s2, 20
	v_cvt_f32_ubyte0_e32 v1, s6
	v_cvt_f32_i32_e32 v0, s4
	v_writelane_b32 v253, s3, 21
	s_and_b64 s[2:3], s[2:3], exec
	s_cselect_b32 s2, 52, 51
	s_mul_i32 s2, s20, s2
	s_cselect_b32 s3, 35, 34
	s_add_i32 s2, s2, s11
	s_mul_hi_i32 s7, s2, 0x78787879
	s_lshr_b32 s8, s7, 31
	s_ashr_i32 s7, s7, 8
	s_add_i32 s7, s7, s8
	s_mul_hi_i32 s8, s2, 0x2aaaaaab
	s_lshr_b32 s9, s8, 31
	s_ashr_i32 s8, s8, 3
	s_add_i32 s8, s8, s9
	s_mul_i32 s9, s7, 0x220
	s_mul_i32 s10, s8, 48
	s_sub_i32 s9, s2, s9
	s_sub_i32 s10, s2, s10
	s_mul_i32 s2, s20, s3
	s_add_i32 s2, s2, s11
	s_mul_hi_i32 s3, s2, 0x78787879
	v_writelane_b32 v253, s11, 22
	s_lshr_b32 s11, s3, 31
	s_ashr_i32 s3, s3, 8
	s_add_i32 s3, s3, s11
	s_ashr_i32 s11, s2, 31
	s_lshr_b32 s11, s11, 27
	s_add_i32 s11, s2, s11
	s_and_b32 s12, s11, 0xffffffe0
	s_mul_i32 s13, s3, 0x220
	s_lshl_b32 s7, s7, 3
	s_sub_i32 s12, s2, s12
	s_sub_i32 s13, s2, s13
	s_sub_i32 s2, 6, s7
	s_lshl_b32 s8, s8, 3
	s_min_u32 s14, s2, 8
	s_sub_i32 s2, 0x44, s8
	v_rcp_iflag_f32_e32 v2, v1
	s_min_u32 s15, s2, 8
	s_ashr_i32 s2, s11, 5
	s_lshl_b32 s11, s2, 3
	s_sub_i32 s2, 0x44, s11
	s_lshl_b32 s17, s3, 3
	s_min_u32 s16, s2, 8
	s_sub_i32 s2, 4, s17
	v_mul_f32_e32 v2, v0, v2
	s_min_u32 s18, s2, 8
	s_ashr_i32 s2, s4, 30
	v_trunc_f32_e32 v2, v2
	s_or_b32 s19, s2, 1
	v_fma_f32 v0, -v2, v1, v0
	v_writelane_b32 v253, s20, 23
	s_lshr_b32 s2, s20, 31
	v_writelane_b32 v253, s2, 24
	v_cmp_ge_f32_e64 s[2:3], |v0|, v1
	v_cvt_i32_f32_e32 v0, v2
	s_and_b64 s[2:3], s[2:3], exec
	v_cvt_f32_ubyte0_e32 v1, s14
	s_cselect_b32 s2, s19, 0
	v_readfirstlane_b32 s3, v0
	v_cvt_f32_i32_e32 v0, s9
	v_rcp_iflag_f32_e32 v2, v1
	s_add_i32 s19, s3, s2
	s_mul_i32 s2, s19, s6
	s_sub_i32 s2, s4, s2
	s_sext_i32_i16 s2, s2
	v_mul_f32_e32 v2, v0, v2
	s_add_i32 s2, s5, s2
	v_trunc_f32_e32 v2, v2
	v_writelane_b32 v253, s2, 25
	s_ashr_i32 s2, s9, 30
	v_fma_f32 v0, -v2, v1, v0
	s_or_b32 s4, s2, 1
	v_cmp_ge_f32_e64 s[2:3], |v0|, v1
	v_cvt_i32_f32_e32 v0, v2
	s_and_b64 s[2:3], s[2:3], exec
	s_cselect_b32 s2, s4, 0
	v_cvt_f32_ubyte0_e32 v1, s15
	v_readfirstlane_b32 s3, v0
	s_add_i32 s2, s3, s2
	s_mul_i32 s3, s2, s14
	s_sub_i32 s3, s9, s3
	s_sext_i32_i16 s3, s3
	v_cvt_f32_i32_e32 v0, s10
	v_rcp_iflag_f32_e32 v2, v1
	s_bfe_i64 s[4:5], s[2:3], 0x100000
	s_lshl_b64 s[4:5], s[4:5], 20
	s_add_i32 s6, s7, s3
	v_writelane_b32 v253, s4, 26
	s_ashr_i32 s7, s6, 31
	v_mul_f32_e32 v2, v0, v2
	v_writelane_b32 v253, s5, 27
	s_mov_b32 s4, s6
	v_writelane_b32 v253, s4, 28
	v_trunc_f32_e32 v2, v2
	v_fma_f32 v0, -v2, v1, v0
	v_writelane_b32 v253, s5, 29
	s_lshl_b64 s[4:5], s[6:7], 20
	v_writelane_b32 v253, s4, 30
	s_ashr_i32 s3, s10, 30
	s_or_b32 s3, s3, 1
	v_writelane_b32 v253, s5, 31
	v_cmp_ge_f32_e64 s[4:5], |v0|, v1
	v_cvt_i32_f32_e32 v0, v2
	s_and_b64 s[4:5], s[4:5], exec
	s_cselect_b32 s3, s3, 0
	v_cvt_f32_ubyte0_e32 v1, s16
	v_readfirstlane_b32 s4, v0
	s_add_i32 s4, s4, s3
	s_mul_i32 s3, s4, s15
	s_sub_i32 s3, s10, s3
	v_cvt_f32_i32_e32 v0, s12
	v_rcp_iflag_f32_e32 v2, v1
	s_bfe_i64 s[6:7], s[4:5], 0x80000
	s_sext_i32_i8 s3, s3
	s_lshl_b64 s[6:7], s[6:7], 18
	s_add_i32 s8, s8, s3
	v_writelane_b32 v253, s6, 32
	s_ashr_i32 s9, s8, 31
	v_mul_f32_e32 v2, v0, v2
	v_writelane_b32 v253, s7, 33
	s_mov_b32 s6, s8
	v_writelane_b32 v253, s6, 34
	v_trunc_f32_e32 v2, v2
	v_fma_f32 v0, -v2, v1, v0
	v_writelane_b32 v253, s7, 35
	s_lshl_b64 s[6:7], s[8:9], 21
	v_writelane_b32 v253, s6, 36
	s_ashr_i32 s3, s12, 30
	s_or_b32 s3, s3, 1
	v_writelane_b32 v253, s7, 37
	v_cmp_ge_f32_e64 s[6:7], |v0|, v1
	v_cvt_i32_f32_e32 v0, v2
	s_and_b64 s[6:7], s[6:7], exec
	s_cselect_b32 s3, s3, 0
	v_cvt_f32_ubyte0_e32 v1, s18
	v_readfirstlane_b32 s5, v0
	s_add_i32 s6, s5, s3
	s_mul_i32 s3, s6, s16
	s_sub_i32 s3, s12, s3
	v_cvt_f32_i32_e32 v0, s13
	v_rcp_iflag_f32_e32 v2, v1
	s_bfe_i64 s[8:9], s[6:7], 0x80000
	s_sext_i32_i8 s3, s3
	s_lshl_b64 s[8:9], s[8:9], 18
	s_add_i32 s10, s11, s3
	v_writelane_b32 v253, s8, 38
	s_load_dword s7, s[0:1], 0x120
	s_ashr_i32 s11, s10, 31
	v_writelane_b32 v253, s9, 39
	s_mov_b32 s8, s10
	v_mul_f32_e32 v2, v0, v2
	v_writelane_b32 v253, s8, 40
	v_trunc_f32_e32 v2, v2
	v_fma_f32 v0, -v2, v1, v0
	v_writelane_b32 v253, s9, 41
	s_lshl_b64 s[8:9], s[10:11], 21
	v_writelane_b32 v253, s8, 42
	s_mul_i32 s5, s23, s22
	s_waitcnt lgkmcnt(0)
	s_mul_i32 s5, s5, s7
	v_writelane_b32 v253, s9, 43
	v_cmp_ge_f32_e64 s[8:9], |v0|, v1
	v_cvt_i32_f32_e32 v0, v2
	s_ashr_i32 s3, s13, 30
	v_writelane_b32 v253, s5, 44
	s_sext_i32_i16 s2, s2
	s_or_b32 s3, s3, 1
	v_writelane_b32 v253, s2, 45
	s_sext_i32_i8 s2, s4
	s_and_b64 s[8:9], s[8:9], exec
	v_writelane_b32 v253, s2, 46
	s_sext_i32_i8 s2, s6
	v_writelane_b32 v253, s2, 47
	s_cselect_b32 s2, s3, 0
	v_readfirstlane_b32 s3, v0
	s_add_i32 s2, s3, s2
	s_mul_i32 s3, s2, s18
	s_sub_i32 s3, s13, s3
	s_sext_i32_i16 s4, s19
	s_sext_i32_i16 s3, s3
	v_writelane_b32 v253, s4, 48
	s_add_i32 s6, s17, s3
	s_sext_i32_i16 s3, s2
	v_writelane_b32 v253, s3, 49
	s_bfe_i64 s[2:3], s[2:3], 0x100000
	s_lshl_b64 s[2:3], s[2:3], 21
	v_writelane_b32 v253, s2, 50
	s_mov_b32 s4, s24
	s_ashr_i32 s5, s24, 31
	v_writelane_b32 v253, s3, 51
	v_writelane_b32 v253, s4, 52
	s_lshl_b32 s2, s33, 12
	s_ashr_i32 s7, s6, 31
	v_writelane_b32 v253, s5, 53
	v_writelane_b32 v253, s2, 54
	s_add_i32 s2, s2, 0xfffc0000
	v_writelane_b32 v253, s2, 55
	s_add_i32 s2, 0, 0x23fc0
	v_writelane_b32 v253, s2, 56
	s_add_i32 s2, 0, 0x23fc4
	v_writelane_b32 v253, s2, 57
	s_add_i32 s2, 0, 0x8100
	v_writelane_b32 v253, s2, 58
	s_mov_b32 s2, s6
	v_writelane_b32 v253, s2, 59
	s_ashr_i32 s31, s30, 31
	s_ashr_i32 s29, s28, 31
	v_writelane_b32 v253, s3, 60
	s_lshl_b64 s[2:3], s[6:7], 18
	v_writelane_b32 v253, s2, 61
	s_ashr_i32 s27, s26, 31
	s_mov_b64 s[12:13], -1
	v_writelane_b32 v253, s3, 62
	s_mov_b32 s2, s30
	v_writelane_b32 v253, s2, 63
	v_mbcnt_lo_u32_b32 v0, -1, 0
	v_mbcnt_hi_u32_b32 v227, -1, v0
	v_writelane_b32 v254, s3, 0
	s_lshl_b64 s[2:3], s[30:31], 2
	v_writelane_b32 v254, s2, 1
	s_mov_b64 s[20:21], 0x80
	s_mov_b64 s[22:23], 0x10000
	v_writelane_b32 v254, s3, 2
	v_writelane_b32 v254, s28, 3
	s_lshl_b64 s[2:3], s[28:29], 13
	s_nop 0
	v_writelane_b32 v254, s29, 4
	v_writelane_b32 v254, s2, 5
	s_nop 1
	v_writelane_b32 v254, s3, 6
	v_writelane_b32 v254, s26, 7
	s_lshl_b64 s[2:3], s[26:27], 13
	s_nop 0
	v_writelane_b32 v254, s27, 8
	v_writelane_b32 v254, s2, 9
	s_nop 1
	v_writelane_b32 v254, s3, 10
	s_lshl_b64 s[2:3], s[4:5], 2
	v_writelane_b32 v254, s2, 11
	s_nop 1
	v_writelane_b32 v254, s3, 12
	v_writelane_b32 v254, s86, 13
	s_branch .LBB0_58

.LBB0_1519:
	s_add_i32 s46, s46, 1
	v_readlane_b32 s2, v252, 63
	s_mul_i32 s2, s46, s2
	s_mul_hi_u32 s3, s46, s33
	s_add_i32 s3, s3, s2
	s_mul_i32 s2, s46, s33
	v_readlane_b32 s11, v253, 14
	s_add_u32 s14, s2, s11
	v_readlane_b32 s2, v252, 62
	s_addc_u32 s15, s3, s2
	s_cmp_eq_u32 s33, 0x100
	s_cbranch_scc0 .Lht1_done
	s_cmp_eq_u32 s24, 0x220
	s_cbranch_scc0 .Lht1_done
	s_cmp_eq_u32 s46, 2
	s_cbranch_scc0 .Lht1_done
	s_cmp_lt_u32 s11, 64
	s_cselect_b32 s2, 0, 0x100000
	s_lshr_b32 s14, s11, 1
	s_addk_i32 s14, 0x200
	s_add_u32 s14, s14, s2
	s_mov_b32 s15, 0
.Lht1_done:
	v_mov_b64_e32 v[0:1], s[24:25]
	v_cmp_ge_i64_e32 vcc, s[14:15], v[0:1]
	v_cmp_lt_i64_e64 s[2:3], s[14:15], v[0:1]
	s_cbranch_vccnz .LBB0_1521
	s_ashr_i32 s10, s14, 31
	s_lshr_b32 s10, s10, 29
	s_add_i32 s10, s14, s10
	s_ashr_i32 s11, s10, 3
	s_and_b32 s10, s10, -8
	s_sub_i32 s10, s14, s10
	s_cmp_lt_i32 s10, 0
	s_cselect_b32 s12, s40, s38
	s_mul_i32 s10, s12, s10
	s_add_i32 s10, s10, s11
	s_ashr_i32 s11, s10, 31
	s_lshr_b32 s11, s11, 26
	s_add_i32 s11, s10, s11
	s_ashr_i32 s12, s11, 6
	s_lshl_b32 s12, s12, 3
	s_sub_i32 s13, s38, s12
	s_min_i32 s13, s13, 8
	s_abs_i32 s14, s13
	v_cvt_f32_u32_e32 v0, s14
	s_sub_i32 s16, 0, s14
	s_andn2_b32 s11, s11, 63
	s_sub_i32 s11, s10, s11
	v_rcp_iflag_f32_e32 v0, v0
	s_abs_i32 s10, s11
	s_xor_b32 s15, s11, s13
	s_ashr_i32 s15, s15, 31
	v_mul_f32_e32 v0, 0x4f7ffffe, v0
	v_cvt_u32_f32_e32 v0, v0
	s_nop 0
	v_readfirstlane_b32 s17, v0
	s_mul_i32 s16, s16, s17
	s_mul_hi_u32 s16, s17, s16
	s_add_i32 s17, s17, s16
	s_mul_hi_u32 s16, s10, s17
	s_mul_i32 s17, s16, s14
	s_sub_i32 s10, s10, s17
	s_add_i32 s30, s16, 1
	s_sub_i32 s17, s10, s14
	s_cmp_ge_u32 s10, s14
	s_cselect_b32 s16, s30, s16
	s_cselect_b32 s10, s17, s10
	s_add_i32 s17, s16, 1
	s_cmp_ge_u32 s10, s14
	s_cselect_b32 s10, s17, s16
	s_xor_b32 s10, s10, s15
	s_sub_i32 s10, s10, s15
	s_mul_i32 s13, s10, s13
	s_sub_i32 s11, s11, s13
	s_add_i32 s12, s11, s12
.LBB0_1521:
	s_ashr_i32 s13, s12, 31
	s_lshl_b64 s[14:15], s[12:13], 22
	s_add_u32 s14, s34, s14
	s_addc_u32 s15, s35, s15
	s_cmp_eq_u32 s33, 0x100
	s_cbranch_scc0 .Lht2_done
	s_cmp_eq_u32 s24, 0x220
	s_cbranch_scc0 .Lht2_done
	s_cmp_eq_u32 s46, 2
	s_cbranch_scc0 .Lht2_done
	v_readlane_b32 s16, v253, 14
	s_nop 0
	s_and_b32 s16, s16, 1
	s_lshl_b32 s16, s16, 21
	s_add_u32 s14, s14, s16
	s_addc_u32 s15, s15, 0
.Lht2_done:
	s_and_b64 s[16:17], s[2:3], exec
	s_cselect_b32 s13, s15, s27
	s_cselect_b32 s48, s14, s26
	s_ashr_i32 s11, s10, 31
	s_lshl_b64 s[16:17], s[10:11], 22
	s_add_u32 s16, s36, s16
	s_addc_u32 s17, s37, s17
	s_and_b64 s[30:31], s[2:3], exec
	s_cselect_b32 s11, s17, s29
	s_cselect_b32 s49, s16, s28
	s_add_u32 s26, s26, 0x200080
	s_addc_u32 s27, s27, 0
	s_add_u32 s50, s28, 0x100
	v_mov_b32_e32 v0, 0
	s_addc_u32 s51, s29, 0
	s_mov_b32 s52, -2
	v_mov_b32_e32 v1, v0
	v_mov_b64_e32 v[2:3], v[0:1]
	v_mov_b64_e32 v[4:5], v[0:1]
	v_mov_b64_e32 v[6:7], v[0:1]
	v_mov_b64_e32 v[8:9], v[0:1]
	v_mov_b64_e32 v[10:11], v[0:1]
	v_mov_b64_e32 v[12:13], v[0:1]
	v_mov_b64_e32 v[14:15], v[0:1]
	v_mov_b64_e32 v[16:17], v[0:1]
	v_mov_b64_e32 v[18:19], v[0:1]
	v_mov_b64_e32 v[20:21], v[0:1]
	v_mov_b64_e32 v[22:23], v[0:1]
	v_mov_b64_e32 v[24:25], v[0:1]
	v_mov_b64_e32 v[26:27], v[0:1]
	v_mov_b64_e32 v[28:29], v[0:1]
	v_mov_b64_e32 v[30:31], v[0:1]
	v_mov_b64_e32 v[32:33], v[0:1]
	v_mov_b64_e32 v[34:35], v[0:1]
	v_mov_b64_e32 v[36:37], v[0:1]
	v_mov_b64_e32 v[38:39], v[0:1]
	v_mov_b64_e32 v[40:41], v[0:1]
	v_mov_b64_e32 v[42:43], v[0:1]
	v_mov_b64_e32 v[44:45], v[0:1]
	v_mov_b64_e32 v[46:47], v[0:1]
	v_mov_b64_e32 v[48:49], v[0:1]
	v_mov_b64_e32 v[50:51], v[0:1]
	v_mov_b64_e32 v[52:53], v[0:1]
	v_mov_b64_e32 v[54:55], v[0:1]
	v_mov_b64_e32 v[56:57], v[0:1]
	v_mov_b64_e32 v[58:59], v[0:1]
	v_mov_b64_e32 v[60:61], v[0:1]
	v_mov_b64_e32 v[62:63], v[0:1]
	v_mov_b64_e32 v[64:65], v[0:1]
	v_mov_b64_e32 v[66:67], v[0:1]
	v_mov_b64_e32 v[68:69], v[0:1]
	v_mov_b64_e32 v[70:71], v[0:1]
	v_mov_b64_e32 v[72:73], v[0:1]
	v_mov_b64_e32 v[74:75], v[0:1]
	v_mov_b64_e32 v[76:77], v[0:1]
	v_mov_b64_e32 v[78:79], v[0:1]
	v_mov_b64_e32 v[80:81], v[0:1]
	v_mov_b64_e32 v[82:83], v[0:1]
	v_mov_b64_e32 v[84:85], v[0:1]
	v_mov_b64_e32 v[86:87], v[0:1]
	v_mov_b64_e32 v[88:89], v[0:1]
	v_mov_b64_e32 v[90:91], v[0:1]
	v_mov_b64_e32 v[92:93], v[0:1]
	v_mov_b64_e32 v[94:95], v[0:1]
	v_mov_b64_e32 v[96:97], v[0:1]
	v_mov_b64_e32 v[98:99], v[0:1]
	v_mov_b64_e32 v[100:101], v[0:1]
	v_mov_b64_e32 v[102:103], v[0:1]
	v_mov_b64_e32 v[104:105], v[0:1]
	v_mov_b64_e32 v[106:107], v[0:1]
	v_mov_b64_e32 v[108:109], v[0:1]
	v_mov_b64_e32 v[110:111], v[0:1]
	v_mov_b64_e32 v[112:113], v[0:1]
	v_mov_b64_e32 v[114:115], v[0:1]
	v_mov_b64_e32 v[116:117], v[0:1]
	v_mov_b64_e32 v[118:119], v[0:1]
	v_mov_b64_e32 v[120:121], v[0:1]
	v_mov_b64_e32 v[122:123], v[0:1]
	v_mov_b64_e32 v[124:125], v[0:1]
	v_mov_b64_e32 v[126:127], v[0:1]
	s_mov_b32 vcc_lo, 0
	s_cmp_eq_u32 s33, 0x100
	s_cbranch_scc0 .Lht3_done
	s_cmp_eq_u32 s24, 0x220
	s_cbranch_scc0 .Lht3_done
	s_cmp_eq_u32 s46, 3
	s_cbranch_scc0 .Lht3_done
	s_mov_b32 vcc_lo, 1
.Lht3_done:
.LBB0_1522:
	s_add_u32 s28, s26, 0xffe00080
	s_addc_u32 s29, s27, -1
	s_add_i32 s53, 0, 0x10000
	s_cmpk_eq_i32 s52, 0x7c
	s_cselect_b32 s31, s13, s29
	s_cselect_b32 s30, s48, s28
	s_cselect_b32 s29, s11, s51
	s_cselect_b32 s28, s49, s50
	s_add_i32 s56, 0, 0x14000
	v_add_u32_e32 v140, s53, v157
	v_add_u32_e32 v154, s56, v157
	ds_read_b128 v[128:131], v140
	ds_read_b128 v[132:135], v140 offset:1024
	ds_read_b128 v[136:139], v140 offset:2048
	ds_read_b128 v[140:143], v140 offset:3072
	ds_read_b128 v[172:175], v154
	ds_read_b128 v[176:179], v154 offset:1024
	ds_read_b128 v[180:183], v154 offset:2048
	ds_read_b128 v[184:187], v154 offset:3072
	v_lshl_add_u64 v[154:155], s[26:27], 0, v[150:151]
	s_add_i32 m0, s19, 0xc000
	ds_read_b128 v[196:199], v159
	ds_read_b128 v[200:203], v159 offset:1024
	ds_read_b128 v[204:207], v159 offset:2048
	ds_read_b128 v[208:211], v159 offset:3072
	ds_read_b128 v[212:215], v159 offset:4096
	ds_read_b128 v[234:237], v159 offset:5120
	ds_read_b128 v[238:241], v159 offset:6144
	ds_read_b128 v[242:245], v159 offset:7168
	global_load_lds_dwordx4 v[154:155], off
	v_lshl_add_u64 v[154:155], s[26:27], 0, v[152:153]
	s_add_i32 m0, s19, 0xe000
	s_nop 0
	global_load_lds_dwordx4 v[154:155], off
	s_waitcnt vmcnt(8)
	s_waitcnt lgkmcnt(0)
	s_barrier
	s_setprio 1
	s_waitcnt lgkmcnt(0)
	v_mfma_f32_16x16x32_bf16 v[124:127], v[128:131], v[196:199], v[124:127]
	v_mfma_f32_16x16x32_bf16 v[120:123], v[136:139], v[196:199], v[120:123]
	v_mfma_f32_16x16x32_bf16 v[116:119], v[128:131], v[204:207], v[116:119]
	v_mfma_f32_16x16x32_bf16 v[108:111], v[136:139], v[204:207], v[108:111]
	v_mfma_f32_16x16x32_bf16 v[92:95], v[128:131], v[212:215], v[92:95]
	v_mfma_f32_16x16x32_bf16 v[88:91], v[136:139], v[212:215], v[88:91]
	v_mfma_f32_16x16x32_bf16 v[84:87], v[128:131], v[238:241], v[84:87]
	v_mfma_f32_16x16x32_bf16 v[76:79], v[136:139], v[238:241], v[76:79]
	v_mfma_f32_16x16x32_bf16 v[124:127], v[132:135], v[200:203], v[124:127]
	v_mfma_f32_16x16x32_bf16 v[120:123], v[140:143], v[200:203], v[120:123]
	v_mfma_f32_16x16x32_bf16 v[116:119], v[132:135], v[208:211], v[116:119]
	v_mfma_f32_16x16x32_bf16 v[108:111], v[140:143], v[208:211], v[108:111]
	v_mfma_f32_16x16x32_bf16 v[92:95], v[132:135], v[234:237], v[92:95]
	v_mfma_f32_16x16x32_bf16 v[88:91], v[140:143], v[234:237], v[88:91]
	v_mfma_f32_16x16x32_bf16 v[84:87], v[132:135], v[242:245], v[84:87]
	v_mfma_f32_16x16x32_bf16 v[76:79], v[140:143], v[242:245], v[76:79]
	s_setprio 0
	s_setprio 1
	v_mfma_f32_16x16x32_bf16 v[112:115], v[172:175], v[196:199], v[112:115]
	v_mfma_f32_16x16x32_bf16 v[104:107], v[180:183], v[196:199], v[104:107]
	v_mfma_f32_16x16x32_bf16 v[100:103], v[172:175], v[204:207], v[100:103]
	v_mfma_f32_16x16x32_bf16 v[96:99], v[180:183], v[204:207], v[96:99]
	v_mfma_f32_16x16x32_bf16 v[80:83], v[172:175], v[212:215], v[80:83]
	v_mfma_f32_16x16x32_bf16 v[72:75], v[180:183], v[212:215], v[72:75]
	v_mfma_f32_16x16x32_bf16 v[68:71], v[172:175], v[238:241], v[68:71]
	v_mfma_f32_16x16x32_bf16 v[64:67], v[180:183], v[238:241], v[64:67]
	v_mfma_f32_16x16x32_bf16 v[112:115], v[176:179], v[200:203], v[112:115]
	v_mfma_f32_16x16x32_bf16 v[104:107], v[184:187], v[200:203], v[104:107]
	v_mfma_f32_16x16x32_bf16 v[100:103], v[176:179], v[208:211], v[100:103]
	v_mfma_f32_16x16x32_bf16 v[96:99], v[184:187], v[208:211], v[96:99]
	v_mfma_f32_16x16x32_bf16 v[80:83], v[176:179], v[234:237], v[80:83]
	v_mfma_f32_16x16x32_bf16 v[72:75], v[184:187], v[234:237], v[72:75]
	v_mfma_f32_16x16x32_bf16 v[68:71], v[176:179], v[242:245], v[68:71]
	v_mfma_f32_16x16x32_bf16 v[64:67], v[184:187], v[242:245], v[64:67]
	s_setprio 0
	s_barrier
	s_add_i32 s53, s53, s39
	v_lshl_add_u64 v[154:155], s[28:29], 0, v[160:161]
	s_mov_b32 m0, s53
	ds_read_b128 v[196:199], v159 offset:16384
	ds_read_b128 v[200:203], v159 offset:17408
	ds_read_b128 v[204:207], v159 offset:18432
	ds_read_b128 v[208:211], v159 offset:19456
	ds_read_b128 v[212:215], v159 offset:20480
	ds_read_b128 v[234:237], v159 offset:21504
	ds_read_b128 v[238:241], v159 offset:22528
	ds_read_b128 v[242:245], v159 offset:23552
	global_load_lds_dwordx4 v[154:155], off
	s_add_i32 m0, s53, 0x2000
	s_add_u32 s54, s28, 0x200000
	v_lshl_add_u64 v[188:189], s[28:29], 0, v[144:145]
	s_addc_u32 s55, s29, 0
	s_add_i32 s53, s56, s39
	global_load_lds_dwordx4 v[188:189], off
	v_lshl_add_u64 v[216:217], s[54:55], 0, v[160:161]
	s_mov_b32 m0, s53
	v_lshl_add_u64 v[246:247], s[30:31], 0, v[146:147]
	global_load_lds_dwordx4 v[216:217], off
	v_lshl_add_u64 v[216:217], s[54:55], 0, v[144:145]
	s_add_i32 m0, s53, 0x2000
	s_nop 0
	global_load_lds_dwordx4 v[216:217], off
	v_lshl_add_u64 v[216:217], s[30:31], 0, v[148:149]
	s_mov_b32 m0, s19
	s_nop 0
	global_load_lds_dwordx4 v[216:217], off
	s_mov_b32 m0, s41
	s_nop 0
	global_load_lds_dwordx4 v[246:247], off
	s_waitcnt vmcnt(8)
	s_waitcnt lgkmcnt(0)
	s_barrier
	s_setprio 1
	s_waitcnt lgkmcnt(0)
	s_cmp_lg_u32 vcc_lo, 0
	s_cbranch_scc1 .Lht_k1
	v_mfma_f32_16x16x32_bf16 v[60:63], v[128:131], v[196:199], v[60:63]
	v_mfma_f32_16x16x32_bf16 v[56:59], v[136:139], v[196:199], v[56:59]
	v_mfma_f32_16x16x32_bf16 v[52:55], v[128:131], v[204:207], v[52:55]
	v_mfma_f32_16x16x32_bf16 v[44:47], v[136:139], v[204:207], v[44:47]
	v_mfma_f32_16x16x32_bf16 v[28:31], v[128:131], v[212:215], v[28:31]
	v_mfma_f32_16x16x32_bf16 v[24:27], v[136:139], v[212:215], v[24:27]
	v_mfma_f32_16x16x32_bf16 v[20:23], v[128:131], v[238:241], v[20:23]
	v_mfma_f32_16x16x32_bf16 v[12:15], v[136:139], v[238:241], v[12:15]
	v_mfma_f32_16x16x32_bf16 v[60:63], v[132:135], v[200:203], v[60:63]
	v_mfma_f32_16x16x32_bf16 v[56:59], v[140:143], v[200:203], v[56:59]
	v_mfma_f32_16x16x32_bf16 v[52:55], v[132:135], v[208:211], v[52:55]
	v_mfma_f32_16x16x32_bf16 v[44:47], v[140:143], v[208:211], v[44:47]
	v_mfma_f32_16x16x32_bf16 v[28:31], v[132:135], v[234:237], v[28:31]
	v_mfma_f32_16x16x32_bf16 v[24:27], v[140:143], v[234:237], v[24:27]
	v_mfma_f32_16x16x32_bf16 v[20:23], v[132:135], v[242:245], v[20:23]
	v_mfma_f32_16x16x32_bf16 v[12:15], v[140:143], v[242:245], v[12:15]
	s_setprio 0
	s_setprio 1
	v_mfma_f32_16x16x32_bf16 v[48:51], v[172:175], v[196:199], v[48:51]
	v_mfma_f32_16x16x32_bf16 v[40:43], v[180:183], v[196:199], v[40:43]
	v_mfma_f32_16x16x32_bf16 v[36:39], v[172:175], v[204:207], v[36:39]
	v_mfma_f32_16x16x32_bf16 v[32:35], v[180:183], v[204:207], v[32:35]
	v_mfma_f32_16x16x32_bf16 v[16:19], v[172:175], v[212:215], v[16:19]
	v_mfma_f32_16x16x32_bf16 v[8:11], v[180:183], v[212:215], v[8:11]
	v_mfma_f32_16x16x32_bf16 v[4:7], v[172:175], v[238:241], v[4:7]
	v_mfma_f32_16x16x32_bf16 v[0:3], v[180:183], v[238:241], v[0:3]
	v_mfma_f32_16x16x32_bf16 v[48:51], v[176:179], v[200:203], v[48:51]
	v_mfma_f32_16x16x32_bf16 v[40:43], v[184:187], v[200:203], v[40:43]
	v_mfma_f32_16x16x32_bf16 v[36:39], v[176:179], v[208:211], v[36:39]
	v_mfma_f32_16x16x32_bf16 v[32:35], v[184:187], v[208:211], v[32:35]
	v_mfma_f32_16x16x32_bf16 v[16:19], v[176:179], v[234:237], v[16:19]
	v_mfma_f32_16x16x32_bf16 v[8:11], v[184:187], v[234:237], v[8:11]
	v_mfma_f32_16x16x32_bf16 v[4:7], v[176:179], v[242:245], v[4:7]
	v_mfma_f32_16x16x32_bf16 v[0:3], v[184:187], v[242:245], v[0:3]
.Lht_k1:
	s_setprio 0
	s_barrier
	s_add_i32 s53, 0, 0x18000
	s_add_i32 s54, 0, 0x1c000
	v_add_u32_e32 v140, s53, v157
	v_add_u32_e32 v162, s54, v157
	ds_read_b128 v[128:131], v140
	ds_read_b128 v[132:135], v140 offset:1024
	ds_read_b128 v[136:139], v140 offset:2048
	ds_read_b128 v[140:143], v140 offset:3072
	ds_read_b128 v[172:175], v162
	ds_read_b128 v[176:179], v162 offset:1024
	ds_read_b128 v[180:183], v162 offset:2048
	ds_read_b128 v[184:187], v162 offset:3072
	s_add_u32 s30, s30, 0x200000
	s_addc_u32 s31, s31, 0
	s_mov_b32 m0, s42
	v_lshl_add_u64 v[248:249], s[30:31], 0, v[148:149]
	ds_read_b128 v[196:199], v159 offset:32768
	ds_read_b128 v[200:203], v159 offset:33792
	ds_read_b128 v[204:207], v159 offset:34816
	ds_read_b128 v[208:211], v159 offset:35840
	ds_read_b128 v[212:215], v159 offset:36864
	ds_read_b128 v[234:237], v159 offset:37888
	ds_read_b128 v[238:241], v159 offset:38912
	ds_read_b128 v[242:245], v159 offset:39936
	global_load_lds_dwordx4 v[248:249], off
	v_lshl_add_u64 v[248:249], s[30:31], 0, v[146:147]
	s_mov_b32 m0, s43
	s_nop 0
	global_load_lds_dwordx4 v[248:249], off
	s_waitcnt vmcnt(8)
	s_waitcnt lgkmcnt(0)
	s_barrier
	s_setprio 1
	s_waitcnt lgkmcnt(0)
	v_mfma_f32_16x16x32_bf16 v[124:127], v[128:131], v[196:199], v[124:127]
	v_mfma_f32_16x16x32_bf16 v[120:123], v[136:139], v[196:199], v[120:123]
	v_mfma_f32_16x16x32_bf16 v[116:119], v[128:131], v[204:207], v[116:119]
	v_mfma_f32_16x16x32_bf16 v[108:111], v[136:139], v[204:207], v[108:111]
	v_mfma_f32_16x16x32_bf16 v[92:95], v[128:131], v[212:215], v[92:95]
	v_mfma_f32_16x16x32_bf16 v[88:91], v[136:139], v[212:215], v[88:91]
	v_mfma_f32_16x16x32_bf16 v[84:87], v[128:131], v[238:241], v[84:87]
	v_mfma_f32_16x16x32_bf16 v[76:79], v[136:139], v[238:241], v[76:79]
	v_mfma_f32_16x16x32_bf16 v[124:127], v[132:135], v[200:203], v[124:127]
	v_mfma_f32_16x16x32_bf16 v[120:123], v[140:143], v[200:203], v[120:123]
	v_mfma_f32_16x16x32_bf16 v[116:119], v[132:135], v[208:211], v[116:119]
	v_mfma_f32_16x16x32_bf16 v[108:111], v[140:143], v[208:211], v[108:111]
	v_mfma_f32_16x16x32_bf16 v[92:95], v[132:135], v[234:237], v[92:95]
	v_mfma_f32_16x16x32_bf16 v[88:91], v[140:143], v[234:237], v[88:91]
	v_mfma_f32_16x16x32_bf16 v[84:87], v[132:135], v[242:245], v[84:87]
	v_mfma_f32_16x16x32_bf16 v[76:79], v[140:143], v[242:245], v[76:79]
	s_setprio 0
	s_setprio 1
	v_mfma_f32_16x16x32_bf16 v[112:115], v[172:175], v[196:199], v[112:115]
	v_mfma_f32_16x16x32_bf16 v[104:107], v[180:183], v[196:199], v[104:107]
	v_mfma_f32_16x16x32_bf16 v[100:103], v[172:175], v[204:207], v[100:103]
	v_mfma_f32_16x16x32_bf16 v[96:99], v[180:183], v[204:207], v[96:99]
	v_mfma_f32_16x16x32_bf16 v[80:83], v[172:175], v[212:215], v[80:83]
	v_mfma_f32_16x16x32_bf16 v[72:75], v[180:183], v[212:215], v[72:75]
	v_mfma_f32_16x16x32_bf16 v[68:71], v[172:175], v[238:241], v[68:71]
	v_mfma_f32_16x16x32_bf16 v[64:67], v[180:183], v[238:241], v[64:67]
	v_mfma_f32_16x16x32_bf16 v[112:115], v[176:179], v[200:203], v[112:115]
	v_mfma_f32_16x16x32_bf16 v[104:107], v[184:187], v[200:203], v[104:107]
	v_mfma_f32_16x16x32_bf16 v[100:103], v[176:179], v[208:211], v[100:103]
	v_mfma_f32_16x16x32_bf16 v[96:99], v[184:187], v[208:211], v[96:99]
	v_mfma_f32_16x16x32_bf16 v[80:83], v[176:179], v[234:237], v[80:83]
	v_mfma_f32_16x16x32_bf16 v[72:75], v[184:187], v[234:237], v[72:75]
	v_mfma_f32_16x16x32_bf16 v[68:71], v[176:179], v[242:245], v[68:71]
	v_mfma_f32_16x16x32_bf16 v[64:67], v[184:187], v[242:245], v[64:67]
	s_setprio 0
	s_barrier
	s_add_i32 s30, s53, s39
	v_lshl_add_u64 v[154:155], v[154:155], 0, s[20:21]
	s_mov_b32 m0, s30
	ds_read_b128 v[196:199], v159 offset:49152
	ds_read_b128 v[200:203], v159 offset:50176
	ds_read_b128 v[204:207], v159 offset:51200
	ds_read_b128 v[208:211], v159 offset:52224
	ds_read_b128 v[212:215], v159 offset:53248
	ds_read_b128 v[234:237], v159 offset:54272
	ds_read_b128 v[238:241], v159 offset:55296
	ds_read_b128 v[242:245], v159 offset:56320
	global_load_lds_dwordx4 v[154:155], off
	s_add_i32 m0, s30, 0x2000
	s_add_u32 s28, s28, 0x200080
	v_lshl_add_u64 v[154:155], v[188:189], 0, s[20:21]
	s_addc_u32 s29, s29, 0
	s_add_i32 s30, s54, s39
	global_load_lds_dwordx4 v[154:155], off
	v_lshl_add_u64 v[154:155], s[28:29], 0, v[160:161]
	s_mov_b32 m0, s30
	s_nop 0
	global_load_lds_dwordx4 v[154:155], off
	v_lshl_add_u64 v[154:155], s[28:29], 0, v[144:145]
	s_add_i32 m0, s30, 0x2000
	s_nop 0
	global_load_lds_dwordx4 v[154:155], off
	v_lshl_add_u64 v[154:155], v[216:217], 0, s[20:21]
	s_mov_b32 m0, s44
	s_nop 0
	global_load_lds_dwordx4 v[154:155], off
	v_lshl_add_u64 v[154:155], v[246:247], 0, s[20:21]
	s_mov_b32 m0, s45
	s_nop 0
	global_load_lds_dwordx4 v[154:155], off
	s_waitcnt vmcnt(8)
	s_waitcnt lgkmcnt(0)
	s_barrier
	s_setprio 1
	s_waitcnt lgkmcnt(0)
	s_cmp_lg_u32 vcc_lo, 0
	s_cbranch_scc1 .Lht_k2
	v_mfma_f32_16x16x32_bf16 v[60:63], v[128:131], v[196:199], v[60:63]
	v_mfma_f32_16x16x32_bf16 v[56:59], v[136:139], v[196:199], v[56:59]
	v_mfma_f32_16x16x32_bf16 v[52:55], v[128:131], v[204:207], v[52:55]
	v_mfma_f32_16x16x32_bf16 v[44:47], v[136:139], v[204:207], v[44:47]
	v_mfma_f32_16x16x32_bf16 v[28:31], v[128:131], v[212:215], v[28:31]
	v_mfma_f32_16x16x32_bf16 v[24:27], v[136:139], v[212:215], v[24:27]
	v_mfma_f32_16x16x32_bf16 v[20:23], v[128:131], v[238:241], v[20:23]
	v_mfma_f32_16x16x32_bf16 v[12:15], v[136:139], v[238:241], v[12:15]
	v_mfma_f32_16x16x32_bf16 v[60:63], v[132:135], v[200:203], v[60:63]
	v_mfma_f32_16x16x32_bf16 v[56:59], v[140:143], v[200:203], v[56:59]
	v_mfma_f32_16x16x32_bf16 v[52:55], v[132:135], v[208:211], v[52:55]
	v_mfma_f32_16x16x32_bf16 v[44:47], v[140:143], v[208:211], v[44:47]
	v_mfma_f32_16x16x32_bf16 v[28:31], v[132:135], v[234:237], v[28:31]
	v_mfma_f32_16x16x32_bf16 v[24:27], v[140:143], v[234:237], v[24:27]
	v_mfma_f32_16x16x32_bf16 v[20:23], v[132:135], v[242:245], v[20:23]
	v_mfma_f32_16x16x32_bf16 v[12:15], v[140:143], v[242:245], v[12:15]
	s_setprio 0
	s_setprio 1
	v_mfma_f32_16x16x32_bf16 v[48:51], v[172:175], v[196:199], v[48:51]
	v_mfma_f32_16x16x32_bf16 v[40:43], v[180:183], v[196:199], v[40:43]
	v_mfma_f32_16x16x32_bf16 v[36:39], v[172:175], v[204:207], v[36:39]
	v_mfma_f32_16x16x32_bf16 v[32:35], v[180:183], v[204:207], v[32:35]
	v_mfma_f32_16x16x32_bf16 v[16:19], v[172:175], v[212:215], v[16:19]
	v_mfma_f32_16x16x32_bf16 v[8:11], v[180:183], v[212:215], v[8:11]
	v_mfma_f32_16x16x32_bf16 v[4:7], v[172:175], v[238:241], v[4:7]
	v_mfma_f32_16x16x32_bf16 v[0:3], v[180:183], v[238:241], v[0:3]
	v_mfma_f32_16x16x32_bf16 v[48:51], v[176:179], v[200:203], v[48:51]
	v_mfma_f32_16x16x32_bf16 v[40:43], v[184:187], v[200:203], v[40:43]
	v_mfma_f32_16x16x32_bf16 v[36:39], v[176:179], v[208:211], v[36:39]
	v_mfma_f32_16x16x32_bf16 v[32:35], v[184:187], v[208:211], v[32:35]
	v_mfma_f32_16x16x32_bf16 v[16:19], v[176:179], v[234:237], v[16:19]
	v_mfma_f32_16x16x32_bf16 v[8:11], v[184:187], v[234:237], v[8:11]
	v_mfma_f32_16x16x32_bf16 v[4:7], v[176:179], v[242:245], v[4:7]
	v_mfma_f32_16x16x32_bf16 v[0:3], v[184:187], v[242:245], v[0:3]
.Lht_k2:
	s_setprio 0
	s_barrier
	s_add_i32 s52, s52, 2
	s_add_u32 s26, s26, 0x100
	s_addc_u32 s27, s27, 0
	s_add_u32 s50, s50, 0x100
	s_addc_u32 s51, s51, 0
	s_cmpk_gt_u32 s52, 0x7d
	s_cbranch_scc0 .LBB0_1522
	s_and_b64 vcc, exec, s[8:9]
	s_cbranch_vccz .LBB0_1525
	s_barrier
.LBB0_1525:
	v_lshl_add_u32 v162, s18, 8, v156
	s_cmp_eq_u32 s33, 0x100
	s_cbranch_scc0 .Lht5_done
	s_cmp_eq_u32 s24, 0x220
	s_cbranch_scc0 .Lht5_done
	s_cmp_eq_u32 s46, 3
	s_cbranch_scc0 .Lht5_done
	v_readlane_b32 s26, v253, 14
	s_nop 0
	s_and_b32 s26, s26, 1
	s_lshl_b32 s26, s26, 7
	s_nop 0
	v_add_u32_e32 v162, s26, v162
.Lht5_done:
	v_min_i32_e32 v129, 0x4000, v162
	v_ashrrev_i32_e32 v129, 12, v129
	s_load_dwordx4 s[28:31], s[0:1], 0xf8
	v_mul_hi_i32_i24_e32 v131, 0xc000, v129
	v_mul_i32_i24_e32 v130, 0xc000, v129
	v_lshl_add_u64 v[130:131], s[6:7], 0, v[130:131]
	s_mov_b64 s[26:27], 0xa000
	v_lshl_add_u64 v[130:131], v[130:131], 0, s[26:27]
	v_readlane_b32 s26, v252, 6
	s_movk_i32 s11, 0x4000
	v_readlane_b32 s27, v252, 7
	v_add_u32_e32 v172, 0xffffc000, v162
	v_ashrrev_i32_e32 v173, 31, v162
	v_cmp_gt_i32_e32 vcc, s11, v162
	v_mov_b32_e32 v192, s27
	s_waitcnt lgkmcnt(0)
	v_mov_b32_e32 v195, s29
	v_mov_b32_e32 v214, s26
	v_mov_b32_e32 v215, s28
	v_or_b32_e32 v196, 16, v162
	v_lshl_or_b32 v128, s47, 8, v158
	v_cndmask_b32_e32 v173, 0, v173, vcc
	v_cndmask_b32_e32 v172, v172, v162, vcc
	v_cndmask_b32_e32 v175, v192, v195, vcc
	v_cndmask_b32_e32 v174, v214, v215, vcc
	v_add_u32_e32 v198, 0xffffc010, v162
	v_ashrrev_i32_e32 v197, 31, v196
	v_cmp_gt_i32_e32 vcc, s11, v196
	v_ashrrev_i32_e32 v129, 31, v128
	v_lshlrev_b64 v[154:155], 2, v[128:129]
	v_cndmask_b32_e32 v197, 0, v197, vcc
	v_cndmask_b32_e32 v196, v198, v196, vcc
	v_or_b32_e32 v128, 0x80, v128
	v_lshlrev_b64 v[172:173], 13, v[172:173]
	v_cndmask_b32_e32 v199, v192, v195, vcc
	v_cndmask_b32_e32 v198, v214, v215, vcc
	v_lshlrev_b64 v[196:197], 13, v[196:197]
	v_lshl_add_u64 v[132:133], v[130:131], 0, v[154:155]
	v_ashrrev_i32_e32 v129, 31, v128
	v_lshl_add_u64 v[172:173], v[174:175], 0, v[172:173]
	v_lshl_add_u64 v[196:197], v[198:199], 0, v[196:197]
	global_load_dwordx4 v[136:139], v[132:133], off offset:16
	global_load_dwordx4 v[140:143], v[132:133], off
	v_lshl_add_u64 v[132:133], v[128:129], 2, v[130:131]
	v_lshl_add_u64 v[188:189], v[172:173], 0, v[154:155]
	v_lshl_add_u64 v[212:213], v[196:197], 0, v[154:155]
	global_load_dwordx4 v[128:131], v[132:133], off offset:16
	s_nop 0
	global_load_dwordx4 v[132:135], v[132:133], off
	s_nop 0
	global_load_dwordx4 v[172:175], v[188:189], off offset:16
	global_load_dwordx4 v[176:179], v[188:189], off
	global_load_dwordx4 v[180:183], v[188:189], off offset:528
	global_load_dwordx4 v[184:187], v[188:189], off offset:512
	global_load_dwordx4 v[196:199], v[212:213], off offset:16
	global_load_dwordx4 v[200:203], v[212:213], off
	global_load_dwordx4 v[204:207], v[212:213], off offset:528
	global_load_dwordx4 v[208:211], v[212:213], off offset:512
	s_waitcnt vmcnt(0)
	v_pk_fma_f32 v[106:107], v[106:107], v[130:131], v[182:183]
	v_pk_fma_f32 v[104:105], v[104:105], v[128:129], v[180:181]
	v_pk_fma_f32 v[126:127], v[126:127], v[142:143], v[178:179]
	v_pk_fma_f32 v[124:125], v[124:125], v[140:141], v[176:177]
	v_pk_fma_f32 v[122:123], v[122:123], v[138:139], v[174:175]
	v_pk_fma_f32 v[120:121], v[120:121], v[136:137], v[172:173]
	v_pk_fma_f32 v[114:115], v[114:115], v[134:135], v[186:187]
	v_pk_fma_f32 v[112:113], v[112:113], v[132:133], v[184:185]
	global_store_dwordx4 v[188:189], v[104:107], off offset:528
	global_store_dwordx4 v[188:189], v[124:127], off
	global_store_dwordx4 v[188:189], v[120:123], off offset:16
	v_pk_fma_f32 v[106:107], v[118:119], v[142:143], v[202:203]
	v_pk_fma_f32 v[104:105], v[116:117], v[140:141], v[200:201]
	global_store_dwordx4 v[188:189], v[112:115], off offset:512
	global_store_dwordx4 v[212:213], v[104:107], off
	v_pk_fma_f32 v[102:103], v[102:103], v[134:135], v[210:211]
	v_pk_fma_f32 v[100:101], v[100:101], v[132:133], v[208:209]
	v_pk_fma_f32 v[106:107], v[110:111], v[138:139], v[198:199]
	v_pk_fma_f32 v[104:105], v[108:109], v[136:137], v[196:197]
	v_pk_fma_f32 v[98:99], v[98:99], v[130:131], v[206:207]
	v_pk_fma_f32 v[96:97], v[96:97], v[128:129], v[204:205]
	global_store_dwordx4 v[212:213], v[104:107], off offset:16
	global_store_dwordx4 v[212:213], v[100:103], off offset:512
	global_store_dwordx4 v[212:213], v[96:99], off offset:528
	s_nop 1
	v_or_b32_e32 v96, 32, v162
	v_add_u32_e32 v98, 0xffffc020, v162
	v_ashrrev_i32_e32 v97, 31, v96
	v_cmp_gt_i32_e32 vcc, s11, v96
	v_or_b32_e32 v112, 48, v162
	v_add_u32_e32 v114, 0xffffc030, v162
	v_cndmask_b32_e32 v97, 0, v97, vcc
	v_cndmask_b32_e32 v96, v98, v96, vcc
	v_cndmask_b32_e32 v99, v192, v195, vcc
	v_cndmask_b32_e32 v98, v214, v215, vcc
	v_ashrrev_i32_e32 v113, 31, v112
	v_cmp_gt_i32_e32 vcc, s11, v112
	v_lshlrev_b64 v[96:97], 13, v[96:97]
	v_lshl_add_u64 v[96:97], v[98:99], 0, v[96:97]
	v_cndmask_b32_e32 v113, 0, v113, vcc
	v_cndmask_b32_e32 v112, v114, v112, vcc
	v_cndmask_b32_e32 v115, v192, v195, vcc
	v_cndmask_b32_e32 v114, v214, v215, vcc
	v_lshlrev_b64 v[112:113], 13, v[112:113]
	v_lshl_add_u64 v[112:113], v[114:115], 0, v[112:113]
	v_lshl_add_u64 v[172:173], v[96:97], 0, v[154:155]
	v_lshl_add_u64 v[174:175], v[112:113], 0, v[154:155]
	global_load_dwordx4 v[96:99], v[172:173], off offset:16
	global_load_dwordx4 v[100:103], v[172:173], off
	global_load_dwordx4 v[104:107], v[172:173], off offset:528
	global_load_dwordx4 v[108:111], v[172:173], off offset:512
	global_load_dwordx4 v[112:115], v[174:175], off offset:16
	global_load_dwordx4 v[116:119], v[174:175], off
	global_load_dwordx4 v[120:123], v[174:175], off offset:528
	global_load_dwordx4 v[124:127], v[174:175], off offset:512
	s_waitcnt vmcnt(5)
	v_pk_fma_f32 v[74:75], v[74:75], v[130:131], v[106:107]
	v_pk_fma_f32 v[72:73], v[72:73], v[128:129], v[104:105]
	v_pk_fma_f32 v[94:95], v[94:95], v[142:143], v[102:103]
	v_pk_fma_f32 v[92:93], v[92:93], v[140:141], v[100:101]
	v_pk_fma_f32 v[90:91], v[90:91], v[138:139], v[98:99]
	v_pk_fma_f32 v[88:89], v[88:89], v[136:137], v[96:97]
	s_waitcnt vmcnt(4)
	v_pk_fma_f32 v[82:83], v[82:83], v[134:135], v[110:111]
	v_pk_fma_f32 v[80:81], v[80:81], v[132:133], v[108:109]
	global_store_dwordx4 v[172:173], v[72:75], off offset:528
	global_store_dwordx4 v[172:173], v[92:95], off
	global_store_dwordx4 v[172:173], v[88:91], off offset:16
	s_waitcnt vmcnt(5)
	v_pk_fma_f32 v[74:75], v[86:87], v[142:143], v[118:119]
	v_pk_fma_f32 v[72:73], v[84:85], v[140:141], v[116:117]
	global_store_dwordx4 v[172:173], v[80:83], off offset:512
	global_store_dwordx4 v[174:175], v[72:75], off
	s_waitcnt vmcnt(5)
	v_pk_fma_f32 v[70:71], v[70:71], v[134:135], v[126:127]
	v_pk_fma_f32 v[68:69], v[68:69], v[132:133], v[124:125]
	v_pk_fma_f32 v[74:75], v[78:79], v[138:139], v[114:115]
	v_pk_fma_f32 v[72:73], v[76:77], v[136:137], v[112:113]
	v_pk_fma_f32 v[66:67], v[66:67], v[130:131], v[122:123]
	v_pk_fma_f32 v[64:65], v[64:65], v[128:129], v[120:121]
	global_store_dwordx4 v[174:175], v[72:75], off offset:16
	global_store_dwordx4 v[174:175], v[68:71], off offset:512
	global_store_dwordx4 v[174:175], v[64:67], off offset:528
	s_cmp_eq_u32 s33, 0x100
	s_cbranch_scc0 .Lht6_cont
	s_cmp_eq_u32 s24, 0x220
	s_cbranch_scc0 .Lht6_cont
	s_cmp_eq_u32 s46, 3
	s_cbranch_scc1 .Lht_epi_end
.Lht6_cont:
	s_nop 1
	v_add_u32_e32 v64, 0x80, v162
	s_movk_i32 s11, 0x3f80
	v_add_u32_e32 v66, 0xffffc080, v162
	v_ashrrev_i32_e32 v65, 31, v64
	v_cmp_gt_i32_e32 vcc, s11, v162
	v_add_u32_e32 v80, 0x90, v162
	s_movk_i32 s11, 0x3f70
	v_cndmask_b32_e32 v65, 0, v65, vcc
	v_cndmask_b32_e32 v64, v66, v64, vcc
	v_cndmask_b32_e32 v67, v192, v195, vcc
	v_cndmask_b32_e32 v66, v214, v215, vcc
	v_add_u32_e32 v82, 0xffffc090, v162
	v_ashrrev_i32_e32 v81, 31, v80
	v_cmp_gt_i32_e32 vcc, s11, v162
	v_lshlrev_b64 v[64:65], 13, v[64:65]
	v_lshl_add_u64 v[64:65], v[66:67], 0, v[64:65]
	v_cndmask_b32_e32 v81, 0, v81, vcc
	v_cndmask_b32_e32 v80, v82, v80, vcc
	v_cndmask_b32_e32 v83, v192, v195, vcc
	v_cndmask_b32_e32 v82, v214, v215, vcc
	v_lshlrev_b64 v[80:81], 13, v[80:81]
	v_lshl_add_u64 v[80:81], v[82:83], 0, v[80:81]
	v_lshl_add_u64 v[96:97], v[64:65], 0, v[154:155]
	v_lshl_add_u64 v[98:99], v[80:81], 0, v[154:155]
	global_load_dwordx4 v[64:67], v[96:97], off offset:16
	global_load_dwordx4 v[68:71], v[96:97], off
	global_load_dwordx4 v[72:75], v[96:97], off offset:528
	global_load_dwordx4 v[76:79], v[96:97], off offset:512
	global_load_dwordx4 v[80:83], v[98:99], off offset:16
	global_load_dwordx4 v[84:87], v[98:99], off
	global_load_dwordx4 v[88:91], v[98:99], off offset:528
	global_load_dwordx4 v[92:95], v[98:99], off offset:512
	s_waitcnt vmcnt(5)
	v_pk_fma_f32 v[42:43], v[42:43], v[130:131], v[74:75]
	v_pk_fma_f32 v[40:41], v[40:41], v[128:129], v[72:73]
	v_pk_fma_f32 v[62:63], v[62:63], v[142:143], v[70:71]
	v_pk_fma_f32 v[60:61], v[60:61], v[140:141], v[68:69]
	v_pk_fma_f32 v[58:59], v[58:59], v[138:139], v[66:67]
	v_pk_fma_f32 v[56:57], v[56:57], v[136:137], v[64:65]
	s_waitcnt vmcnt(4)
	v_pk_fma_f32 v[50:51], v[50:51], v[134:135], v[78:79]
	v_pk_fma_f32 v[48:49], v[48:49], v[132:133], v[76:77]
	global_store_dwordx4 v[96:97], v[40:43], off offset:528
	global_store_dwordx4 v[96:97], v[60:63], off
	global_store_dwordx4 v[96:97], v[56:59], off offset:16
	s_waitcnt vmcnt(5)
	v_pk_fma_f32 v[42:43], v[54:55], v[142:143], v[86:87]
	v_pk_fma_f32 v[40:41], v[52:53], v[140:141], v[84:85]
	global_store_dwordx4 v[96:97], v[48:51], off offset:512
	global_store_dwordx4 v[98:99], v[40:43], off
	s_waitcnt vmcnt(5)
	v_pk_fma_f32 v[38:39], v[38:39], v[134:135], v[94:95]
	v_pk_fma_f32 v[36:37], v[36:37], v[132:133], v[92:93]
	v_pk_fma_f32 v[42:43], v[46:47], v[138:139], v[82:83]
	v_pk_fma_f32 v[40:41], v[44:45], v[136:137], v[80:81]
	v_pk_fma_f32 v[34:35], v[34:35], v[130:131], v[90:91]
	v_pk_fma_f32 v[32:33], v[32:33], v[128:129], v[88:89]
	global_store_dwordx4 v[98:99], v[40:43], off offset:16
	global_store_dwordx4 v[98:99], v[36:39], off offset:512
	global_store_dwordx4 v[98:99], v[32:35], off offset:528
	s_nop 1
	v_add_u32_e32 v32, 0xa0, v162
	s_movk_i32 s11, 0x3f60
	v_add_u32_e32 v34, 0xffffc0a0, v162
	v_ashrrev_i32_e32 v33, 31, v32
	v_cmp_gt_i32_e32 vcc, s11, v162
	v_add_u32_e32 v48, 0xb0, v162
	s_movk_i32 s11, 0x3f50
	v_cndmask_b32_e32 v33, 0, v33, vcc
	v_cndmask_b32_e32 v32, v34, v32, vcc
	v_cndmask_b32_e32 v35, v192, v195, vcc
	v_cndmask_b32_e32 v34, v214, v215, vcc
	v_add_u32_e32 v50, 0xffffc0b0, v162
	v_ashrrev_i32_e32 v49, 31, v48
	v_cmp_gt_i32_e32 vcc, s11, v162
	v_lshlrev_b64 v[32:33], 13, v[32:33]
	v_lshl_add_u64 v[32:33], v[34:35], 0, v[32:33]
	v_cndmask_b32_e32 v49, 0, v49, vcc
	v_cndmask_b32_e32 v48, v50, v48, vcc
	v_cndmask_b32_e32 v51, v192, v195, vcc
	v_cndmask_b32_e32 v50, v214, v215, vcc
	v_lshlrev_b64 v[48:49], 13, v[48:49]
	v_lshl_add_u64 v[48:49], v[50:51], 0, v[48:49]
	v_lshl_add_u64 v[64:65], v[32:33], 0, v[154:155]
	v_lshl_add_u64 v[66:67], v[48:49], 0, v[154:155]
	global_load_dwordx4 v[32:35], v[64:65], off offset:16
	global_load_dwordx4 v[36:39], v[64:65], off
	global_load_dwordx4 v[40:43], v[64:65], off offset:528
	global_load_dwordx4 v[44:47], v[64:65], off offset:512
	global_load_dwordx4 v[48:51], v[66:67], off offset:16
	global_load_dwordx4 v[52:55], v[66:67], off
	global_load_dwordx4 v[56:59], v[66:67], off offset:528
	global_load_dwordx4 v[60:63], v[66:67], off offset:512
	s_waitcnt vmcnt(5)
	v_pk_fma_f32 v[10:11], v[10:11], v[130:131], v[42:43]
	v_pk_fma_f32 v[8:9], v[8:9], v[128:129], v[40:41]
	v_pk_fma_f32 v[30:31], v[30:31], v[142:143], v[38:39]
	v_pk_fma_f32 v[28:29], v[28:29], v[140:141], v[36:37]
	v_pk_fma_f32 v[26:27], v[26:27], v[138:139], v[34:35]
	v_pk_fma_f32 v[24:25], v[24:25], v[136:137], v[32:33]
	s_waitcnt vmcnt(4)
	v_pk_fma_f32 v[18:19], v[18:19], v[134:135], v[46:47]
	v_pk_fma_f32 v[16:17], v[16:17], v[132:133], v[44:45]
	global_store_dwordx4 v[64:65], v[8:11], off offset:528
	global_store_dwordx4 v[64:65], v[28:31], off
	global_store_dwordx4 v[64:65], v[24:27], off offset:16
	s_waitcnt vmcnt(5)
	v_pk_fma_f32 v[10:11], v[22:23], v[142:143], v[54:55]
	v_pk_fma_f32 v[8:9], v[20:21], v[140:141], v[52:53]
	global_store_dwordx4 v[64:65], v[16:19], off offset:512
	global_store_dwordx4 v[66:67], v[8:11], off
	s_waitcnt vmcnt(5)
	v_pk_fma_f32 v[6:7], v[6:7], v[134:135], v[62:63]
	v_pk_fma_f32 v[4:5], v[4:5], v[132:133], v[60:61]
	v_pk_fma_f32 v[10:11], v[14:15], v[138:139], v[50:51]
	v_pk_fma_f32 v[8:9], v[12:13], v[136:137], v[48:49]
	v_pk_fma_f32 v[2:3], v[2:3], v[130:131], v[58:59]
	v_pk_fma_f32 v[0:1], v[0:1], v[128:129], v[56:57]
	global_store_dwordx4 v[66:67], v[8:11], off offset:16
	global_store_dwordx4 v[66:67], v[4:7], off offset:512
	global_store_dwordx4 v[66:67], v[0:3], off offset:528
.Lht_epi_end:
	s_andn2_b64 vcc, exec, s[2:3]
	s_mov_b64 s[2:3], -1
	s_cbranch_vccnz .LBB0_1518
	s_andn2_b64 vcc, exec, s[4:5]
	s_cbranch_vccnz .LBB0_1517
	s_barrier
	s_branch .LBB0_1517

.LBB0_1529:
	v_readlane_b32 s2, v253, 15
	v_readlane_b32 s3, v253, 16
	s_and_b64 s[2:3], s[2:3], s[36:37]
	s_andn2_b64 vcc, exec, s[2:3]
	s_cbranch_vccnz .LBB0_1625
	s_load_dwordx4 s[4:7], s[0:1], 0xf8
	v_mov_b32_e32 v44, v190
	s_mov_b32 s60, s86
	s_mov_b32 s2, 7
	s_waitcnt lgkmcnt(0)
	s_mov_b64 s[16:17], s[6:7]
	s_ashr_i32 s3, s2, 31
	s_sub_i32 s24, s60, 64
	s_lshl_b64 s[2:3], s[2:3], 3
	s_add_u32 s2, s0, s2
	s_addc_u32 s3, s1, s3
	s_load_dwordx2 s[2:3], s[2:3], 0x0
	v_ashrrev_i32_e32 v0, 6, v44
	v_lshl_add_u32 v14, s24, 3, v0
	s_waitcnt lgkmcnt(0)
	s_add_u32 s18, s2, 0x58a0000
	s_mov_b32 s2, 0x87c0
	s_addc_u32 s19, s3, 0
	v_cmp_gt_i32_e32 vcc, s2, v14
	s_and_saveexec_b64 s[26:27], vcc
	s_cbranch_execz .LBB0_1567
	s_add_u32 s28, s16, 0x3280000
	s_addc_u32 s29, s17, 0
	s_add_u32 s30, s16, 0x3080000
	s_addc_u32 s31, s17, 0
	s_add_u32 s34, s16, 0x2f00000
	s_addc_u32 s35, s17, 0
	s_add_u32 s36, s16, 0x4880000
	s_addc_u32 s37, s17, 0
	s_add_u32 s38, s16, 0x4080000
	v_lshl_add_u32 v1, v0, 14, 0
	s_addc_u32 s39, s17, 0
	v_bfe_u32 v15, v44, 5, 1
	v_and_b32_e32 v0, 31, v44
	s_add_u32 s40, s16, 0x30f14d00
	v_mul_u32_u24_e32 v2, 0x84, v15
	v_lshlrev_b32_e32 v3, 2, v0
	s_addc_u32 s41, s17, 0
	v_add3_u32 v16, v1, v2, v3
	v_and_b32_e32 v2, 7, v44
	v_bfe_u32 v17, v44, 3, 3
	s_add_u32 s42, s16, 0x3480000
	v_mul_u32_u24_e32 v3, 0x420, v2
	v_lshlrev_b32_e32 v4, 2, v17
	v_lshlrev_b32_e32 v2, 3, v2
	s_addc_u32 s43, s17, 0
	v_add3_u32 v18, v1, v3, v4
	s_mov_b64 s[44:45], 0
	v_lshlrev_b32_e32 v160, 2, v0
	v_lshlrev_b32_e32 v0, 1, v2
	s_branch .LBB0_1534

.LBB0_1572:
	s_or_b64 exec, exec, s[2:3]
	s_mov_b32 s2, 8
	s_ashr_i32 s3, s2, 31
	s_lshl_b64 s[2:3], s[2:3], 3
	s_add_u32 s2, s0, s2
	s_addc_u32 s3, s1, s3
	s_load_dwordx2 s[2:3], s[2:3], 0x0
	s_movk_i32 s4, 0x1100
	v_cmp_gt_i32_e32 vcc, s4, v4
	v_ashrrev_i32_e32 v5, 31, v4
	s_and_saveexec_b64 s[4:5], vcc
	v_readlane_b32 s18, v253, 52
	v_readlane_b32 s19, v253, 53
	s_cbranch_execz .LBB0_1595
	v_lshl_add_u32 v0, s60, 9, v44
	s_waitcnt lgkmcnt(0)
	s_add_u32 s6, s2, 0xb140
	v_add_u32_e32 v2, 0xffff7bc0, v0
	v_lshl_add_u64 v[0:1], v[4:5], 2, s[16:17]
	s_mov_b64 s[8:9], 0x8880000
	s_addc_u32 s7, s3, 0
	v_lshl_add_u64 v[0:1], v[0:1], 0, s[8:9]
	s_mov_b64 s[8:9], 0
	v_mov_b32_e32 v3, v4
	s_branch .LBB0_1575

.LBB0_1606:
	s_or_b64 exec, exec, s[4:5]
	s_cmpk_gt_i32 s60, 0xbf
	s_cbranch_scc1 .LBB0_1624
	v_and_b32_e32 v0, 0xff, v44
	v_ashrrev_i32_e32 v45, 8, v44
	v_mov_b32_e32 v1, 0x80
	v_lshlrev_b32_e32 v160, 1, v0
	v_bfe_u32 v2, v44, 4, 4
	v_and_b32_e32 v4, 15, v44
	v_lshl_add_u32 v46, v45, 6, v1
	v_lshl_add_u32 v48, v0, 2, 0
	v_lshl_add_u64 v[0:1], s[16:17], 0, v[160:161]
	s_mov_b64 s[6:7], 0xc88bc00
	v_lshl_add_u64 v[0:1], v[0:1], 0, s[6:7]
	v_cmp_eq_u32_e64 s[6:7], v2, v4
	v_or_b32_e32 v49, 0x400, v2
	v_cmp_gt_u32_e64 s[8:9], s87, v44
	v_mov_b32_e32 v2, 0xffffe000
	v_mov_b32_e32 v5, 0x2000
	v_cndmask_b32_e64 v2, v2, v5, s[8:9]
	v_lshlrev_b32_e32 v5, 4, v44
	s_movk_i32 s2, 0x1000
	v_and_b32_e32 v160, 0xf00, v5
	v_lshlrev_b32_e32 v4, 3, v4
	v_mov_b32_e32 v5, v161
	v_cmp_gt_i32_e64 s[2:3], s2, v44
	v_lshl_add_u32 v47, v45, 14, 0
	v_cmp_eq_u32_e64 s[4:5], 1, v45
	v_cndmask_b32_e64 v3, -1, 0, s[8:9]
	v_lshl_add_u32 v50, v44, 3, 0
	v_lshl_add_u64 v[4:5], s[12:13], 0, v[4:5]
	s_branch .LBB0_1611
